# prologue weight conversion: the 8 (or 16) serialized element loads per tile issued together, one wait
# speedup vs baseline: 1.0220x; 1.0220x over previous
; DI unsigned pk2(float a, float b) { f32x2 v = {a, b}; return __builtin_bit_cast(unsigned, __builtin_convertvector(v, bf2_t)); }
; DI int v2logical(int v) { const int m = (v >> 4) & 3, fq = (v >> 2) & 3, j = v & 3; return (v & ~63) + 32 * (m >> 1) + 8 * fq + 4 * (m & 1) + j; }
; DI void convert_job(const float* __restrict__ src, int ld, int K, int Nv, int mode, int coloff, const float* __restrict__ rowscale,
;                     bf16_t* __restrict__ dst, char* lds) {
;     ...
;     for (int tile = blockIdx.x; tile < tiles_k * tiles_v; tile += gridDim.x) {
;         const int tk = tile % tiles_k, tv = tile / tiles_k, k0 = tk * 64, v0 = tv * 64;
;         {
;             const int v = t & 63, kk = t >> 6;
;             int L = v2logical(v0 + v);
;             if (mode) { const int g = (v0 + v) >= 2048 ? ((v0 + v) - 2048) >> 9 : -1; if (g == 2 || g == 6) L = v0 + v; }
;             const int col = mode ? inproj_actual(L) : coloff + L;
; #pragma unroll
;             for (int i = 0; i < 8; ++i) {
;                 const int k = kk + 8 * i;
;                 float xv = src[(size_t)(k0 + k) * ld + col];
;                 if (rowscale) xv *= rowscale[k0 + k];
;                 tl[k][v] = xv;
;             }
;         }
;         __syncthreads();
;         {
;             const int vv = t >> 3, kc = t & 7;
;             u32x4 o;
;             o[0] = pk2(tl[8 * kc + 0][vv], tl[8 * kc + 1][vv]); o[1] = pk2(tl[8 * kc + 2][vv], tl[8 * kc + 3][vv]);
;             o[2] = pk2(tl[8 * kc + 4][vv], tl[8 * kc + 5][vv]); o[3] = pk2(tl[8 * kc + 6][vv], tl[8 * kc + 7][vv]);
;             *(u32x4*)(dst + (size_t)(v0 + vv) * K + k0 + 8 * kc) = o;
;         }
;         __syncthreads();
;     }
.Lcv1_join:
	s_waitcnt lgkmcnt(0)
	s_barrier
	ds_read2_b32 v[2:3], v12 offset1:65
	ds_read2_b32 v[4:5], v12 offset0:130 offset1:195
	v_add_u32_e32 v6, 0x400, v12
	s_sub_i32 s6, 0, s20
	s_add_i32 s6, s23, s6
	s_waitcnt lgkmcnt(1)
	v_cvt_pk_bf16_f32 v2, v2, v3
	s_waitcnt lgkmcnt(0)
	v_cvt_pk_bf16_f32 v3, v4, v5
	ds_read2_b32 v[4:5], v6 offset0:4 offset1:69
	ds_read2_b32 v[6:7], v6 offset0:134 offset1:199
	s_ashr_i32 s7, s6, 31
	s_add_i32 s24, s24, s3
	s_add_i32 s23, s23, s22
	s_waitcnt lgkmcnt(1)
	v_cvt_pk_bf16_f32 v4, v4, v5
	s_waitcnt lgkmcnt(0)
	v_cvt_pk_bf16_f32 v5, v6, v7
	v_add_u32_e32 v6, s25, v11
	v_ashrrev_i32_e32 v7, 31, v6
	v_lshlrev_b64 v[6:7], 11, v[6:7]
	v_lshl_add_u64 v[6:7], s[16:17], 0, v[6:7]
	v_lshl_add_u64 v[6:7], s[6:7], 1, v[6:7]
	v_lshl_add_u64 v[6:7], v[6:7], 0, v[0:1]
	s_cmpk_lt_i32 s24, 0x600
	global_store_dwordx4 v[6:7], v[2:5], off
	s_barrier
	s_cbranch_scc0 .LBB0_378

; DI int tid() { int t = __builtin_amdgcn_workitem_id_x(); asm volatile("" : "+v"(t)); return t; }
; DI int v2logical(int v) { const int m = (v >> 4) & 3, fq = (v >> 2) & 3, j = v & 3; return (v & ~63) + 32 * (m >> 1) + 8 * fq + 4 * (m & 1) + j; }
; DI int inproj_actual(int L) {
;     if (L < 1024) { const int i = L >> 8, w = L & 255; return (w < 128 ? 512 : 1024) + 128 * i + (w & 127); }
;     if (L < 2048) { L -= 1024; const int i = L >> 8, w = L & 255; return (w < 128 ? 0 : 1536) + 128 * i + (w & 127); }
;     return L;
; }
; DI void convert_job(const float* __restrict__ src, int ld, int K, int Nv, int mode, int coloff, const float* __restrict__ rowscale,
;                     bf16_t* __restrict__ dst, char* lds) {
;     float (*tl)[65] = (float (*)[65])lds;
;     const int t = tid();
;     const int tiles_k = K >> 6, tiles_v = Nv >> 6;
;     for (int tile = blockIdx.x; tile < tiles_k * tiles_v; tile += gridDim.x) {
;         const int tk = tile % tiles_k, tv = tile / tiles_k, k0 = tk * 64, v0 = tv * 64;
;         {
;             const int v = t & 63, kk = t >> 6;
;             int L = v2logical(v0 + v);
;             if (mode) { const int g = (v0 + v) >= 2048 ? ((v0 + v) - 2048) >> 9 : -1; if (g == 2 || g == 6) L = v0 + v; }
;             const int col = mode ? inproj_actual(L) : coloff + L;
; #pragma unroll
;             for (int i = 0; i < 8; ++i) {
;                 const int k = kk + 8 * i;
;                 float xv = src[(size_t)(k0 + k) * ld + col];
;                 if (rowscale) xv *= rowscale[k0 + k];
;                 tl[k][v] = xv;
;             }
.LBB0_360:
	s_andn2_saveexec_b64 s[6:7], s[6:7]
	v_and_b32_e32 v3, 0x80, v2
	v_cmp_eq_u32_e32 vcc, 0, v3
	v_mov_b32_e32 v3, 0x400
	v_mov_b32_e32 v4, 0x200
	v_cndmask_b32_e32 v3, v3, v4, vcc
	v_ashrrev_i32_e32 v4, 1, v2
	v_and_b32_e32 v4, 0xffffff80, v4
	v_add_u32_e32 v3, v3, v4
	v_and_or_b32 v2, v2, s33, v3
	s_or_b64 exec, exec, s[6:7]
	s_lshl_b32 s20, s26, 10
	v_ashrrev_i32_e32 v3, 31, v2
	s_sub_i32 s6, s23, s20
	v_lshl_add_u64 v[2:3], v[2:3], 2, s[12:13]
	v_add_u32_e32 v4, s6, v9
	v_ashrrev_i32_e32 v5, 31, v4
	v_lshl_add_u64 v[6:7], v[4:5], 2, s[14:15]
	v_mad_i64_i32 v[56:57], s[26:27], v4, s85, v[2:3]
	global_load_dword v40, v[56:57], off
	v_add_u32_e32 v5, 8, v4
	v_mad_i64_i32 v[56:57], s[26:27], v5, s85, v[2:3]
	global_load_dword v41, v[56:57], off
	v_add_u32_e32 v5, 16, v4
	v_mad_i64_i32 v[56:57], s[26:27], v5, s85, v[2:3]
	global_load_dword v42, v[56:57], off
	v_add_u32_e32 v5, 24, v4
	v_mad_i64_i32 v[56:57], s[26:27], v5, s85, v[2:3]
	global_load_dword v43, v[56:57], off
	v_add_u32_e32 v5, 32, v4
	v_mad_i64_i32 v[56:57], s[26:27], v5, s85, v[2:3]
	global_load_dword v44, v[56:57], off
	v_add_u32_e32 v5, 40, v4
	v_mad_i64_i32 v[56:57], s[26:27], v5, s85, v[2:3]
	global_load_dword v45, v[56:57], off
	v_add_u32_e32 v5, 48, v4
	v_mad_i64_i32 v[56:57], s[26:27], v5, s85, v[2:3]
	global_load_dword v46, v[56:57], off
	v_add_u32_e32 v5, 56, v4
	v_mad_i64_i32 v[56:57], s[26:27], v5, s85, v[2:3]
	global_load_dword v47, v[56:57], off
	s_andn2_b64 vcc, exec, s[0:1]
	s_cbranch_vccnz .Lcv1_nors
	global_load_dword v48, v[6:7], off
	global_load_dword v49, v[6:7], off offset:32
	global_load_dword v50, v[6:7], off offset:64
	global_load_dword v51, v[6:7], off offset:96
	global_load_dword v52, v[6:7], off offset:128
	global_load_dword v53, v[6:7], off offset:160
	global_load_dword v54, v[6:7], off offset:192
	global_load_dword v55, v[6:7], off offset:224
	s_waitcnt vmcnt(0)
	v_mul_f32_e32 v40, v40, v48
	v_mul_f32_e32 v41, v41, v49
	v_mul_f32_e32 v42, v42, v50
	v_mul_f32_e32 v43, v43, v51
	v_mul_f32_e32 v44, v44, v52
	v_mul_f32_e32 v45, v45, v53
	v_mul_f32_e32 v46, v46, v54
	v_mul_f32_e32 v47, v47, v55
.Lcv1_nors:
	s_waitcnt vmcnt(0)
	ds_write_b32 v13, v40
	ds_write_b32 v13, v41 offset:2080
	ds_write_b32 v13, v42 offset:4160
	ds_write_b32 v13, v43 offset:6240
	ds_write_b32 v13, v44 offset:8320
	ds_write_b32 v13, v45 offset:10400
	ds_write_b32 v13, v46 offset:12480
	ds_write_b32 v13, v47 offset:14560
	s_branch .Lcv1_join

; DI unsigned pk2(float a, float b) { f32x2 v = {a, b}; return __builtin_bit_cast(unsigned, __builtin_convertvector(v, bf2_t)); }
; DI int v2logical(int v) { const int m = (v >> 4) & 3, fq = (v >> 2) & 3, j = v & 3; return (v & ~63) + 32 * (m >> 1) + 8 * fq + 4 * (m & 1) + j; }
; DI void convert_job(const float* __restrict__ src, int ld, int K, int Nv, int mode, int coloff, const float* __restrict__ rowscale,
;                     bf16_t* __restrict__ dst, char* lds) {
;     ...
;     for (int tile = blockIdx.x; tile < tiles_k * tiles_v; tile += gridDim.x) {
;         const int tk = tile % tiles_k, tv = tile / tiles_k, k0 = tk * 64, v0 = tv * 64;
;         {
;             const int v = t & 63, kk = t >> 6;
;             int L = v2logical(v0 + v);
;             if (mode) { const int g = (v0 + v) >= 2048 ? ((v0 + v) - 2048) >> 9 : -1; if (g == 2 || g == 6) L = v0 + v; }
;             const int col = mode ? inproj_actual(L) : coloff + L;
; #pragma unroll
;             for (int i = 0; i < 8; ++i) {
;                 const int k = kk + 8 * i;
;                 float xv = src[(size_t)(k0 + k) * ld + col];
;                 if (rowscale) xv *= rowscale[k0 + k];
;                 tl[k][v] = xv;
;             }
;         }
;         __syncthreads();
;         {
;             const int vv = t >> 3, kc = t & 7;
;             u32x4 o;
;             o[0] = pk2(tl[8 * kc + 0][vv], tl[8 * kc + 1][vv]); o[1] = pk2(tl[8 * kc + 2][vv], tl[8 * kc + 3][vv]);
;             o[2] = pk2(tl[8 * kc + 4][vv], tl[8 * kc + 5][vv]); o[3] = pk2(tl[8 * kc + 6][vv], tl[8 * kc + 7][vv]);
;             *(u32x4*)(dst + (size_t)(v0 + vv) * K + k0 + 8 * kc) = o;
;         }
;         __syncthreads();
;     }
.Lcv2_join:
	s_waitcnt lgkmcnt(0)
	s_barrier
	ds_read2_b32 v[2:3], v10 offset1:65
	ds_read2_b32 v[4:5], v10 offset0:130 offset1:195
	v_add_u32_e32 v6, 0x400, v10
	s_sub_i32 s6, 0, s25
	s_add_i32 s6, s22, s6
	s_waitcnt lgkmcnt(1)
	v_cvt_pk_bf16_f32 v2, v2, v3
	s_waitcnt lgkmcnt(0)
	v_cvt_pk_bf16_f32 v3, v4, v5
	ds_read2_b32 v[4:5], v6 offset0:4 offset1:69
	ds_read2_b32 v[6:7], v6 offset0:134 offset1:199
	s_ashr_i32 s7, s6, 31
	s_add_i32 s23, s23, s20
	s_add_i32 s22, s22, s21
	s_waitcnt lgkmcnt(1)
	v_cvt_pk_bf16_f32 v4, v4, v5
	s_waitcnt lgkmcnt(0)
	v_cvt_pk_bf16_f32 v5, v6, v7
	v_add_u32_e32 v6, s24, v9
	v_ashrrev_i32_e32 v7, 31, v6
	v_lshlrev_b64 v[6:7], 11, v[6:7]
	v_lshl_add_u64 v[6:7], s[16:17], 0, v[6:7]
	v_lshl_add_u64 v[6:7], s[6:7], 1, v[6:7]
	v_lshl_add_u64 v[6:7], v[6:7], 0, v[0:1]
	s_cmpk_lt_i32 s23, 0x300
	global_store_dwordx4 v[6:7], v[2:5], off
	s_barrier
	s_cbranch_scc0 .LBB0_397
.LBB0_381:
	s_ashr_i32 s6, s23, 31
	s_lshr_b32 s6, s6, 28
	s_add_i32 s6, s23, s6
	s_ashr_i32 s6, s6, 4
	s_lshl_b32 s24, s6, 6
	v_or_b32_e32 v2, s24, v12
	v_ashrrev_i32_e32 v3, 31, v2
	s_lshl_b32 s25, s6, 10
	v_lshl_add_u64 v[2:3], v[2:3], 2, s[12:13]
	s_mov_b64 s[6:7], 0x6000
	v_lshl_add_u64 v[2:3], v[2:3], 0, s[6:7]
	s_sub_i32 s6, s22, s25
	v_add_u32_e32 v4, s6, v8
	v_ashrrev_i32_e32 v5, 31, v4
	v_lshl_add_u64 v[6:7], v[4:5], 2, s[14:15]
	v_mad_i64_i32 v[56:57], s[26:27], v4, s85, v[2:3]
	global_load_dword v40, v[56:57], off
	v_add_u32_e32 v5, 8, v4
	v_mad_i64_i32 v[56:57], s[26:27], v5, s85, v[2:3]
	global_load_dword v41, v[56:57], off
	v_add_u32_e32 v5, 16, v4
	v_mad_i64_i32 v[56:57], s[26:27], v5, s85, v[2:3]
	global_load_dword v42, v[56:57], off
	v_add_u32_e32 v5, 24, v4
	v_mad_i64_i32 v[56:57], s[26:27], v5, s85, v[2:3]
	global_load_dword v43, v[56:57], off
	v_add_u32_e32 v5, 32, v4
	v_mad_i64_i32 v[56:57], s[26:27], v5, s85, v[2:3]
	global_load_dword v44, v[56:57], off
	v_add_u32_e32 v5, 40, v4
	v_mad_i64_i32 v[56:57], s[26:27], v5, s85, v[2:3]
	global_load_dword v45, v[56:57], off
	v_add_u32_e32 v5, 48, v4
	v_mad_i64_i32 v[56:57], s[26:27], v5, s85, v[2:3]
	global_load_dword v46, v[56:57], off
	v_add_u32_e32 v5, 56, v4
	v_mad_i64_i32 v[56:57], s[26:27], v5, s85, v[2:3]
	global_load_dword v47, v[56:57], off
	s_andn2_b64 vcc, exec, s[0:1]
	s_cbranch_vccnz .Lcv2_nors
	global_load_dword v48, v[6:7], off
	global_load_dword v49, v[6:7], off offset:32
	global_load_dword v50, v[6:7], off offset:64
	global_load_dword v51, v[6:7], off offset:96
	global_load_dword v52, v[6:7], off offset:128
	global_load_dword v53, v[6:7], off offset:160
	global_load_dword v54, v[6:7], off offset:192
	global_load_dword v55, v[6:7], off offset:224
	s_waitcnt vmcnt(0)
	v_mul_f32_e32 v40, v40, v48
	v_mul_f32_e32 v41, v41, v49
	v_mul_f32_e32 v42, v42, v50
	v_mul_f32_e32 v43, v43, v51
	v_mul_f32_e32 v44, v44, v52
	v_mul_f32_e32 v45, v45, v53
	v_mul_f32_e32 v46, v46, v54
	v_mul_f32_e32 v47, v47, v55
.Lcv2_nors:
	s_waitcnt vmcnt(0)
	ds_write_b32 v11, v40
	ds_write_b32 v11, v41 offset:2080
	ds_write_b32 v11, v42 offset:4160
	ds_write_b32 v11, v43 offset:6240
	ds_write_b32 v11, v44 offset:8320
	ds_write_b32 v11, v45 offset:10400
	ds_write_b32 v11, v46 offset:12480
	ds_write_b32 v11, v47 offset:14560
	s_branch .Lcv2_join

; DI unsigned pk2(float a, float b) { f32x2 v = {a, b}; return __builtin_bit_cast(unsigned, __builtin_convertvector(v, bf2_t)); }
; DI int v2logical(int v) { const int m = (v >> 4) & 3, fq = (v >> 2) & 3, j = v & 3; return (v & ~63) + 32 * (m >> 1) + 8 * fq + 4 * (m & 1) + j; }
; DI void convert_job(const float* __restrict__ src, int ld, int K, int Nv, int mode, int coloff, const float* __restrict__ rowscale,
;                     bf16_t* __restrict__ dst, char* lds) {
;     ...
;     for (int tile = blockIdx.x; tile < tiles_k * tiles_v; tile += gridDim.x) {
;         const int tk = tile % tiles_k, tv = tile / tiles_k, k0 = tk * 64, v0 = tv * 64;
;         {
;             const int v = t & 63, kk = t >> 6;
;             int L = v2logical(v0 + v);
;             if (mode) { const int g = (v0 + v) >= 2048 ? ((v0 + v) - 2048) >> 9 : -1; if (g == 2 || g == 6) L = v0 + v; }
;             const int col = mode ? inproj_actual(L) : coloff + L;
; #pragma unroll
;             for (int i = 0; i < 8; ++i) {
;                 const int k = kk + 8 * i;
;                 float xv = src[(size_t)(k0 + k) * ld + col];
;                 if (rowscale) xv *= rowscale[k0 + k];
;                 tl[k][v] = xv;
;             }
;         }
;         __syncthreads();
;         {
;             const int vv = t >> 3, kc = t & 7;
;             u32x4 o;
;             o[0] = pk2(tl[8 * kc + 0][vv], tl[8 * kc + 1][vv]); o[1] = pk2(tl[8 * kc + 2][vv], tl[8 * kc + 3][vv]);
;             o[2] = pk2(tl[8 * kc + 4][vv], tl[8 * kc + 5][vv]); o[3] = pk2(tl[8 * kc + 6][vv], tl[8 * kc + 7][vv]);
;             *(u32x4*)(dst + (size_t)(v0 + vv) * K + k0 + 8 * kc) = o;
;         }
;         __syncthreads();
;     }
.LBB0_399:
	s_ashr_i32 s20, s25, 31
	s_lshr_b32 s20, s20, 29
	s_add_i32 s20, s25, s20
	s_ashr_i32 s21, s20, 3
	s_lshl_b32 s20, s21, 9
	s_sub_i32 s20, s24, s20
	s_lshl_b32 s21, s21, 6
	v_or_b32_e32 v2, s21, v8
	v_add_u32_e32 v10, s20, v4
	v_ashrrev_i32_e32 v3, 31, v2
	v_ashrrev_i32_e32 v11, 31, v10
	v_lshl_add_u64 v[2:3], v[2:3], 2, s[14:15]
	v_lshlrev_b64 v[12:13], 12, v[10:11]
	v_lshl_add_u64 v[12:13], v[2:3], 0, v[12:13]
	global_load_dword v40, v[12:13], off
	v_add_u32_e32 v12, 8, v10
	v_ashrrev_i32_e32 v13, 31, v12
	v_lshlrev_b64 v[12:13], 12, v[12:13]
	v_lshl_add_u64 v[12:13], v[2:3], 0, v[12:13]
	s_add_i32 s25, s25, s22
	s_add_i32 s24, s24, s23
	global_load_dword v41, v[12:13], off
	v_add_u32_e32 v12, 16, v10
	v_ashrrev_i32_e32 v13, 31, v12
	v_lshlrev_b64 v[12:13], 12, v[12:13]
	v_lshl_add_u64 v[12:13], v[2:3], 0, v[12:13]
	global_load_dword v42, v[12:13], off
	v_add_u32_e32 v12, 24, v10
	v_ashrrev_i32_e32 v13, 31, v12
	v_lshlrev_b64 v[12:13], 12, v[12:13]
	v_lshl_add_u64 v[12:13], v[2:3], 0, v[12:13]
	global_load_dword v43, v[12:13], off
	v_add_u32_e32 v12, 32, v10
	v_ashrrev_i32_e32 v13, 31, v12
	v_lshlrev_b64 v[12:13], 12, v[12:13]
	v_lshl_add_u64 v[12:13], v[2:3], 0, v[12:13]
	global_load_dword v44, v[12:13], off
	v_add_u32_e32 v12, 40, v10
	v_ashrrev_i32_e32 v13, 31, v12
	v_lshlrev_b64 v[12:13], 12, v[12:13]
	v_lshl_add_u64 v[12:13], v[2:3], 0, v[12:13]
	global_load_dword v45, v[12:13], off
	v_add_u32_e32 v12, 48, v10
	v_add_u32_e32 v10, 56, v10
	v_ashrrev_i32_e32 v13, 31, v12
	v_ashrrev_i32_e32 v11, 31, v10
	v_lshlrev_b64 v[12:13], 12, v[12:13]
	v_lshlrev_b64 v[10:11], 12, v[10:11]
	v_lshl_add_u64 v[12:13], v[2:3], 0, v[12:13]
	v_lshl_add_u64 v[2:3], v[2:3], 0, v[10:11]
	global_load_dword v46, v[2:3], off
	global_load_dword v47, v[12:13], off
	s_waitcnt vmcnt(0)
	ds_write_b32 v7, v40
	ds_write_b32 v7, v41 offset:2080
	ds_write_b32 v7, v42 offset:4160
	ds_write_b32 v7, v43 offset:6240
	ds_write_b32 v7, v44 offset:8320
	ds_write_b32 v7, v45 offset:10400
	ds_write_b32 v7, v46 offset:14560
	ds_write_b32 v7, v47 offset:12480
	s_waitcnt lgkmcnt(0)
	s_barrier
	ds_read2_b32 v[2:3], v6 offset1:65
	v_add_u32_e32 v9, 0x400, v6
	s_waitcnt lgkmcnt(0)
	v_cvt_pk_bf16_f32 v10, v2, v3
	ds_read2_b32 v[2:3], v6 offset0:130 offset1:195
	s_waitcnt lgkmcnt(0)
	v_cvt_pk_bf16_f32 v11, v2, v3
	ds_read2_b32 v[2:3], v9 offset0:4 offset1:69
	s_waitcnt lgkmcnt(0)
	v_cvt_pk_bf16_f32 v12, v2, v3
	ds_read2_b32 v[2:3], v9 offset0:134 offset1:199
	s_waitcnt lgkmcnt(0)
	v_cvt_pk_bf16_f32 v13, v2, v3
	v_add_u32_e32 v2, s21, v5
	v_ashrrev_i32_e32 v3, 31, v2
	v_lshlrev_b64 v[2:3], 10, v[2:3]
	v_lshl_add_u64 v[2:3], s[16:17], 0, v[2:3]
	s_ashr_i32 s21, s20, 31
	v_lshl_add_u64 v[2:3], s[20:21], 1, v[2:3]
	v_lshl_add_u64 v[2:3], v[2:3], 0, v[0:1]
	s_cmpk_lt_i32 s25, 0x80
	global_store_dwordx4 v[2:3], v[10:13], off
	s_barrier
	s_cbranch_scc1 .LBB0_399
	v_readlane_b32 s28, v254, 1
	s_mov_b32 s30, 0x6dc9c883
	v_readlane_b32 s29, v254, 2
	s_mov_b32 s38, 0x10000
	s_mov_b32 s39, 0x14000
	s_mov_b32 s40, 0x18000
	s_mov_b32 s41, 0x1c000
	s_mov_b64 s[46:47], 0x1b00180
	s_mov_b32 s31, 0x3fc45f30
	v_readlane_b32 s48, v255, 22

; DI unsigned pk2(float a, float b) { f32x2 v = {a, b}; return __builtin_bit_cast(unsigned, __builtin_convertvector(v, bf2_t)); }
; DI int v2logical(int v) { const int m = (v >> 4) & 3, fq = (v >> 2) & 3, j = v & 3; return (v & ~63) + 32 * (m >> 1) + 8 * fq + 4 * (m & 1) + j; }
; DI void convert_job(const float* __restrict__ src, int ld, int K, int Nv, int mode, int coloff, const float* __restrict__ rowscale,
;                     bf16_t* __restrict__ dst, char* lds) {
;     ...
;     for (int tile = blockIdx.x; tile < tiles_k * tiles_v; tile += gridDim.x) {
;         const int tk = tile % tiles_k, tv = tile / tiles_k, k0 = tk * 64, v0 = tv * 64;
;         {
;             const int v = t & 63, kk = t >> 6;
;             int L = v2logical(v0 + v);
;             if (mode) { const int g = (v0 + v) >= 2048 ? ((v0 + v) - 2048) >> 9 : -1; if (g == 2 || g == 6) L = v0 + v; }
;             const int col = mode ? inproj_actual(L) : coloff + L;
; #pragma unroll
;             for (int i = 0; i < 8; ++i) {
;                 const int k = kk + 8 * i;
;                 float xv = src[(size_t)(k0 + k) * ld + col];
;                 if (rowscale) xv *= rowscale[k0 + k];
;                 tl[k][v] = xv;
;             }
;         }
;         __syncthreads();
;         {
;             const int vv = t >> 3, kc = t & 7;
;             u32x4 o;
;             o[0] = pk2(tl[8 * kc + 0][vv], tl[8 * kc + 1][vv]); o[1] = pk2(tl[8 * kc + 2][vv], tl[8 * kc + 3][vv]);
;             o[2] = pk2(tl[8 * kc + 4][vv], tl[8 * kc + 5][vv]); o[3] = pk2(tl[8 * kc + 6][vv], tl[8 * kc + 7][vv]);
;             *(u32x4*)(dst + (size_t)(v0 + vv) * K + k0 + 8 * kc) = o;
;         }
;         __syncthreads();
;     }
.LBB0_407:
	s_ashr_i32 s14, s21, 31
	s_lshr_b32 s14, s14, 29
	s_add_i32 s14, s21, s14
	s_ashr_i32 s15, s14, 3
	s_lshl_b32 s14, s15, 9
	s_sub_i32 s14, s20, s14
	s_lshl_b32 s15, s15, 6
	v_or_b32_e32 v2, s15, v8
	v_add_u32_e32 v10, s14, v4
	v_ashrrev_i32_e32 v3, 31, v2
	v_ashrrev_i32_e32 v11, 31, v10
	v_lshl_add_u64 v[2:3], v[2:3], 2, s[6:7]
	v_lshlrev_b64 v[12:13], 12, v[10:11]
	v_lshl_add_u64 v[12:13], v[2:3], 0, v[12:13]
	global_load_dword v40, v[12:13], off
	v_add_u32_e32 v12, 8, v10
	v_ashrrev_i32_e32 v13, 31, v12
	v_lshlrev_b64 v[12:13], 12, v[12:13]
	v_lshl_add_u64 v[12:13], v[2:3], 0, v[12:13]
	s_add_i32 s21, s21, s16
	s_add_i32 s20, s20, s17
	global_load_dword v41, v[12:13], off
	v_add_u32_e32 v12, 16, v10
	v_ashrrev_i32_e32 v13, 31, v12
	v_lshlrev_b64 v[12:13], 12, v[12:13]
	v_lshl_add_u64 v[12:13], v[2:3], 0, v[12:13]
	global_load_dword v42, v[12:13], off
	v_add_u32_e32 v12, 24, v10
	v_ashrrev_i32_e32 v13, 31, v12
	v_lshlrev_b64 v[12:13], 12, v[12:13]
	v_lshl_add_u64 v[12:13], v[2:3], 0, v[12:13]
	global_load_dword v43, v[12:13], off
	v_add_u32_e32 v12, 32, v10
	v_ashrrev_i32_e32 v13, 31, v12
	v_lshlrev_b64 v[12:13], 12, v[12:13]
	v_lshl_add_u64 v[12:13], v[2:3], 0, v[12:13]
	global_load_dword v44, v[12:13], off
	v_add_u32_e32 v12, 40, v10
	v_ashrrev_i32_e32 v13, 31, v12
	v_lshlrev_b64 v[12:13], 12, v[12:13]
	v_lshl_add_u64 v[12:13], v[2:3], 0, v[12:13]
	global_load_dword v45, v[12:13], off
	v_add_u32_e32 v12, 48, v10
	v_add_u32_e32 v10, 56, v10
	v_ashrrev_i32_e32 v13, 31, v12
	v_ashrrev_i32_e32 v11, 31, v10
	v_lshlrev_b64 v[12:13], 12, v[12:13]
	v_lshlrev_b64 v[10:11], 12, v[10:11]
	v_lshl_add_u64 v[12:13], v[2:3], 0, v[12:13]
	v_lshl_add_u64 v[2:3], v[2:3], 0, v[10:11]
	global_load_dword v46, v[2:3], off
	global_load_dword v47, v[12:13], off
	s_waitcnt vmcnt(0)
	ds_write_b32 v7, v40
	ds_write_b32 v7, v41 offset:2080
	ds_write_b32 v7, v42 offset:4160
	ds_write_b32 v7, v43 offset:6240
	ds_write_b32 v7, v44 offset:8320
	ds_write_b32 v7, v45 offset:10400
	ds_write_b32 v7, v46 offset:14560
	ds_write_b32 v7, v47 offset:12480
	s_waitcnt lgkmcnt(0)
	s_barrier
	ds_read2_b32 v[2:3], v6 offset1:65
	v_add_u32_e32 v9, 0x400, v6
	s_waitcnt lgkmcnt(0)
	v_cvt_pk_bf16_f32 v10, v2, v3
	ds_read2_b32 v[2:3], v6 offset0:130 offset1:195
	s_waitcnt lgkmcnt(0)
	v_cvt_pk_bf16_f32 v11, v2, v3
	ds_read2_b32 v[2:3], v9 offset0:4 offset1:69
	s_waitcnt lgkmcnt(0)
	v_cvt_pk_bf16_f32 v12, v2, v3
	ds_read2_b32 v[2:3], v9 offset0:134 offset1:199
	s_waitcnt lgkmcnt(0)
	v_cvt_pk_bf16_f32 v13, v2, v3
	v_add_u32_e32 v2, s15, v5
	v_ashrrev_i32_e32 v3, 31, v2
	v_lshlrev_b64 v[2:3], 10, v[2:3]
	v_lshl_add_u64 v[2:3], s[12:13], 0, v[2:3]
	s_ashr_i32 s15, s14, 31
	v_lshl_add_u64 v[2:3], s[14:15], 1, v[2:3]
	v_lshl_add_u64 v[2:3], v[2:3], 0, v[0:1]
	s_cmpk_lt_i32 s21, 0x80
	global_store_dwordx4 v[2:3], v[10:13], off
	s_barrier
	s_cbranch_scc1 .LBB0_407
	v_readlane_b32 s28, v254, 1
	s_mov_b32 s30, 0x6dc9c883
	v_readlane_b32 s29, v254, 2
	s_mov_b32 s38, 0x10000
	s_mov_b32 s39, 0x14000
	s_mov_b32 s40, 0x18000
	s_mov_b32 s41, 0x1c000
	s_mov_b64 s[46:47], 0x1b00180
	s_mov_b32 s31, 0x3fc45f30
	v_readlane_b32 s48, v255, 22

; DI unsigned pk2(float a, float b) { f32x2 v = {a, b}; return __builtin_bit_cast(unsigned, __builtin_convertvector(v, bf2_t)); }
; DI int v2logical(int v) { const int m = (v >> 4) & 3, fq = (v >> 2) & 3, j = v & 3; return (v & ~63) + 32 * (m >> 1) + 8 * fq + 4 * (m & 1) + j; }
; DI void convert_job(const float* __restrict__ src, int ld, int K, int Nv, int mode, int coloff, const float* __restrict__ rowscale,
;                     bf16_t* __restrict__ dst, char* lds) {
;     ...
;     for (int tile = blockIdx.x; tile < tiles_k * tiles_v; tile += gridDim.x) {
;         const int tk = tile % tiles_k, tv = tile / tiles_k, k0 = tk * 64, v0 = tv * 64;
;         {
;             const int v = t & 63, kk = t >> 6;
;             int L = v2logical(v0 + v);
;             if (mode) { const int g = (v0 + v) >= 2048 ? ((v0 + v) - 2048) >> 9 : -1; if (g == 2 || g == 6) L = v0 + v; }
;             const int col = mode ? inproj_actual(L) : coloff + L;
; #pragma unroll
;             for (int i = 0; i < 8; ++i) {
;                 const int k = kk + 8 * i;
;                 float xv = src[(size_t)(k0 + k) * ld + col];
;                 if (rowscale) xv *= rowscale[k0 + k];
;                 tl[k][v] = xv;
;             }
;         }
;         __syncthreads();
;         {
;             const int vv = t >> 3, kc = t & 7;
;             u32x4 o;
;             o[0] = pk2(tl[8 * kc + 0][vv], tl[8 * kc + 1][vv]); o[1] = pk2(tl[8 * kc + 2][vv], tl[8 * kc + 3][vv]);
;             o[2] = pk2(tl[8 * kc + 4][vv], tl[8 * kc + 5][vv]); o[3] = pk2(tl[8 * kc + 6][vv], tl[8 * kc + 7][vv]);
;             *(u32x4*)(dst + (size_t)(v0 + vv) * K + k0 + 8 * kc) = o;
;         }
;         __syncthreads();
;     }
.LBB0_411:
	s_ashr_i32 s20, s25, 31
	s_lshr_b32 s20, s20, 28
	s_add_i32 s20, s25, s20
	s_ashr_i32 s21, s20, 4
	s_lshl_b32 s20, s21, 10
	s_sub_i32 s20, s24, s20
	s_lshl_b32 s21, s21, 6
	v_or_b32_e32 v2, s21, v8
	v_add_u32_e32 v10, s20, v4
	v_ashrrev_i32_e32 v3, 31, v2
	v_ashrrev_i32_e32 v11, 31, v10
	v_lshl_add_u64 v[2:3], v[2:3], 2, s[14:15]
	v_lshlrev_b64 v[12:13], 12, v[10:11]
	v_lshl_add_u64 v[12:13], v[2:3], 0, v[12:13]
	global_load_dword v40, v[12:13], off
	v_add_u32_e32 v12, 8, v10
	v_ashrrev_i32_e32 v13, 31, v12
	v_lshlrev_b64 v[12:13], 12, v[12:13]
	v_lshl_add_u64 v[12:13], v[2:3], 0, v[12:13]
	s_add_i32 s25, s25, s22
	s_add_i32 s24, s24, s23
	global_load_dword v41, v[12:13], off
	v_add_u32_e32 v12, 16, v10
	v_ashrrev_i32_e32 v13, 31, v12
	v_lshlrev_b64 v[12:13], 12, v[12:13]
	v_lshl_add_u64 v[12:13], v[2:3], 0, v[12:13]
	global_load_dword v42, v[12:13], off
	v_add_u32_e32 v12, 24, v10
	v_ashrrev_i32_e32 v13, 31, v12
	v_lshlrev_b64 v[12:13], 12, v[12:13]
	v_lshl_add_u64 v[12:13], v[2:3], 0, v[12:13]
	global_load_dword v43, v[12:13], off
	v_add_u32_e32 v12, 32, v10
	v_ashrrev_i32_e32 v13, 31, v12
	v_lshlrev_b64 v[12:13], 12, v[12:13]
	v_lshl_add_u64 v[12:13], v[2:3], 0, v[12:13]
	global_load_dword v44, v[12:13], off
	v_add_u32_e32 v12, 40, v10
	v_ashrrev_i32_e32 v13, 31, v12
	v_lshlrev_b64 v[12:13], 12, v[12:13]
	v_lshl_add_u64 v[12:13], v[2:3], 0, v[12:13]
	global_load_dword v45, v[12:13], off
	v_add_u32_e32 v12, 48, v10
	v_add_u32_e32 v10, 56, v10
	v_ashrrev_i32_e32 v13, 31, v12
	v_ashrrev_i32_e32 v11, 31, v10
	v_lshlrev_b64 v[12:13], 12, v[12:13]
	v_lshlrev_b64 v[10:11], 12, v[10:11]
	v_lshl_add_u64 v[12:13], v[2:3], 0, v[12:13]
	v_lshl_add_u64 v[2:3], v[2:3], 0, v[10:11]
	global_load_dword v46, v[2:3], off
	global_load_dword v47, v[12:13], off
	s_waitcnt vmcnt(0)
	ds_write_b32 v7, v40
	ds_write_b32 v7, v41 offset:2080
	ds_write_b32 v7, v42 offset:4160
	ds_write_b32 v7, v43 offset:6240
	ds_write_b32 v7, v44 offset:8320
	ds_write_b32 v7, v45 offset:10400
	ds_write_b32 v7, v46 offset:14560
	ds_write_b32 v7, v47 offset:12480
	s_waitcnt lgkmcnt(0)
	s_barrier
	ds_read2_b32 v[2:3], v6 offset1:65
	v_add_u32_e32 v9, 0x400, v6
	s_waitcnt lgkmcnt(0)
	v_cvt_pk_bf16_f32 v10, v2, v3
	ds_read2_b32 v[2:3], v6 offset0:130 offset1:195
	s_waitcnt lgkmcnt(0)
	v_cvt_pk_bf16_f32 v11, v2, v3
	ds_read2_b32 v[2:3], v9 offset0:4 offset1:69
	s_waitcnt lgkmcnt(0)
	v_cvt_pk_bf16_f32 v12, v2, v3
	ds_read2_b32 v[2:3], v9 offset0:134 offset1:199
	s_waitcnt lgkmcnt(0)
	v_cvt_pk_bf16_f32 v13, v2, v3
	v_add_u32_e32 v2, s21, v5
	v_ashrrev_i32_e32 v3, 31, v2
	v_lshlrev_b64 v[2:3], 11, v[2:3]
	v_lshl_add_u64 v[2:3], s[16:17], 0, v[2:3]
	s_ashr_i32 s21, s20, 31
	v_lshl_add_u64 v[2:3], s[20:21], 1, v[2:3]
	v_lshl_add_u64 v[2:3], v[2:3], 0, v[0:1]
	s_cmpk_lt_i32 s25, 0x100
	global_store_dwordx4 v[2:3], v[10:13], off
	s_barrier
	s_cbranch_scc1 .LBB0_411

; DI unsigned pk2(float a, float b) { f32x2 v = {a, b}; return __builtin_bit_cast(unsigned, __builtin_convertvector(v, bf2_t)); }
; DI int v2logical(int v) { const int m = (v >> 4) & 3, fq = (v >> 2) & 3, j = v & 3; return (v & ~63) + 32 * (m >> 1) + 8 * fq + 4 * (m & 1) + j; }
; DI void convert_job(const float* __restrict__ src, int ld, int K, int Nv, int mode, int coloff, const float* __restrict__ rowscale,
;                     bf16_t* __restrict__ dst, char* lds) {
;     ...
;     for (int tile = blockIdx.x; tile < tiles_k * tiles_v; tile += gridDim.x) {
;         const int tk = tile % tiles_k, tv = tile / tiles_k, k0 = tk * 64, v0 = tv * 64;
;         {
;             const int v = t & 63, kk = t >> 6;
;             int L = v2logical(v0 + v);
;             if (mode) { const int g = (v0 + v) >= 2048 ? ((v0 + v) - 2048) >> 9 : -1; if (g == 2 || g == 6) L = v0 + v; }
;             const int col = mode ? inproj_actual(L) : coloff + L;
; #pragma unroll
;             for (int i = 0; i < 8; ++i) {
;                 const int k = kk + 8 * i;
;                 float xv = src[(size_t)(k0 + k) * ld + col];
;                 if (rowscale) xv *= rowscale[k0 + k];
;                 tl[k][v] = xv;
;             }
;         }
;         __syncthreads();
;         {
;             const int vv = t >> 3, kc = t & 7;
;             u32x4 o;
;             o[0] = pk2(tl[8 * kc + 0][vv], tl[8 * kc + 1][vv]); o[1] = pk2(tl[8 * kc + 2][vv], tl[8 * kc + 3][vv]);
;             o[2] = pk2(tl[8 * kc + 4][vv], tl[8 * kc + 5][vv]); o[3] = pk2(tl[8 * kc + 6][vv], tl[8 * kc + 7][vv]);
;             *(u32x4*)(dst + (size_t)(v0 + vv) * K + k0 + 8 * kc) = o;
;         }
;         __syncthreads();
;     }
.Lcv7_join:
	s_waitcnt lgkmcnt(0)
	s_barrier
	ds_read2_b32 v[2:3], v10 offset1:65
	ds_read2_b32 v[4:5], v10 offset0:130 offset1:195
	v_add_u32_e32 v6, 0x400, v10
	s_sub_i32 s6, 0, s25
	s_add_i32 s6, s22, s6
	s_waitcnt lgkmcnt(1)
	v_cvt_pk_bf16_f32 v2, v2, v3
	s_waitcnt lgkmcnt(0)
	v_cvt_pk_bf16_f32 v3, v4, v5
	ds_read2_b32 v[4:5], v6 offset0:4 offset1:69
	ds_read2_b32 v[6:7], v6 offset0:134 offset1:199
	s_ashr_i32 s7, s6, 31
	s_add_i32 s23, s23, s20
	s_add_i32 s22, s22, s21
	s_waitcnt lgkmcnt(1)
	v_cvt_pk_bf16_f32 v4, v4, v5
	s_waitcnt lgkmcnt(0)
	v_cvt_pk_bf16_f32 v5, v6, v7
	v_add_u32_e32 v6, s24, v9
	v_ashrrev_i32_e32 v7, 31, v6
	v_lshlrev_b64 v[6:7], 11, v[6:7]
	v_lshl_add_u64 v[6:7], s[16:17], 0, v[6:7]
	v_lshl_add_u64 v[6:7], s[6:7], 1, v[6:7]
	v_lshl_add_u64 v[6:7], v[6:7], 0, v[0:1]
	s_cmpk_lt_i32 s23, 0x100
	global_store_dwordx4 v[6:7], v[2:5], off
	s_barrier
	s_cbranch_scc0 .LBB0_431
.LBB0_415:
	s_ashr_i32 s6, s23, 31
	s_lshr_b32 s6, s6, 28
	s_add_i32 s6, s23, s6
	s_ashr_i32 s6, s6, 4
	s_lshl_b32 s25, s6, 10
	s_lshl_b32 s24, s6, 6
	s_sub_i32 s6, s22, s25
	v_or_b32_e32 v2, s24, v12
	v_add_u32_e32 v6, s6, v8
	v_ashrrev_i32_e32 v3, 31, v2
	v_ashrrev_i32_e32 v7, 31, v6
	v_lshl_add_u64 v[2:3], v[2:3], 2, s[14:15]
	v_lshl_add_u64 v[4:5], v[6:7], 2, s[10:11]
	v_mov_b32_e32 v14, v6
	v_ashrrev_i32_e32 v15, 31, v14
	v_lshlrev_b64 v[14:15], 12, v[14:15]
	v_lshl_add_u64 v[56:57], v[2:3], 0, v[14:15]
	global_load_dword v40, v[56:57], off
	v_add_u32_e32 v14, 8, v6
	v_ashrrev_i32_e32 v15, 31, v14
	v_lshlrev_b64 v[14:15], 12, v[14:15]
	v_lshl_add_u64 v[56:57], v[2:3], 0, v[14:15]
	global_load_dword v41, v[56:57], off
	v_add_u32_e32 v14, 16, v6
	v_ashrrev_i32_e32 v15, 31, v14
	v_lshlrev_b64 v[14:15], 12, v[14:15]
	v_lshl_add_u64 v[56:57], v[2:3], 0, v[14:15]
	global_load_dword v42, v[56:57], off
	v_add_u32_e32 v14, 24, v6
	v_ashrrev_i32_e32 v15, 31, v14
	v_lshlrev_b64 v[14:15], 12, v[14:15]
	v_lshl_add_u64 v[56:57], v[2:3], 0, v[14:15]
	global_load_dword v43, v[56:57], off
	v_add_u32_e32 v14, 32, v6
	v_ashrrev_i32_e32 v15, 31, v14
	v_lshlrev_b64 v[14:15], 12, v[14:15]
	v_lshl_add_u64 v[56:57], v[2:3], 0, v[14:15]
	global_load_dword v44, v[56:57], off
	v_add_u32_e32 v14, 40, v6
	v_ashrrev_i32_e32 v15, 31, v14
	v_lshlrev_b64 v[14:15], 12, v[14:15]
	v_lshl_add_u64 v[56:57], v[2:3], 0, v[14:15]
	global_load_dword v45, v[56:57], off
	v_add_u32_e32 v14, 48, v6
	v_ashrrev_i32_e32 v15, 31, v14
	v_lshlrev_b64 v[14:15], 12, v[14:15]
	v_lshl_add_u64 v[56:57], v[2:3], 0, v[14:15]
	global_load_dword v46, v[56:57], off
	v_add_u32_e32 v14, 56, v6
	v_ashrrev_i32_e32 v15, 31, v14
	v_lshlrev_b64 v[14:15], 12, v[14:15]
	v_lshl_add_u64 v[56:57], v[2:3], 0, v[14:15]
	global_load_dword v47, v[56:57], off
	s_andn2_b64 vcc, exec, s[66:67]
	s_cbranch_vccnz .Lcv7_nors
	global_load_dword v48, v[4:5], off
	global_load_dword v49, v[4:5], off offset:32
	global_load_dword v50, v[4:5], off offset:64
	global_load_dword v51, v[4:5], off offset:96
	global_load_dword v52, v[4:5], off offset:128
	global_load_dword v53, v[4:5], off offset:160
	global_load_dword v54, v[4:5], off offset:192
	global_load_dword v55, v[4:5], off offset:224
	s_waitcnt vmcnt(0)
	v_mul_f32_e32 v40, v40, v48
	v_mul_f32_e32 v41, v41, v49
	v_mul_f32_e32 v42, v42, v50
	v_mul_f32_e32 v43, v43, v51
	v_mul_f32_e32 v44, v44, v52
	v_mul_f32_e32 v45, v45, v53
	v_mul_f32_e32 v46, v46, v54
	v_mul_f32_e32 v47, v47, v55

; DI unsigned pk2(float a, float b) { f32x2 v = {a, b}; return __builtin_bit_cast(unsigned, __builtin_convertvector(v, bf2_t)); }
; DI int v2logical(int v) { const int m = (v >> 4) & 3, fq = (v >> 2) & 3, j = v & 3; return (v & ~63) + 32 * (m >> 1) + 8 * fq + 4 * (m & 1) + j; }
; DI void convert_job(const float* __restrict__ src, int ld, int K, int Nv, int mode, int coloff, const float* __restrict__ rowscale,
;                     bf16_t* __restrict__ dst, char* lds) {
;     ...
;     for (int tile = blockIdx.x; tile < tiles_k * tiles_v; tile += gridDim.x) {
;         const int tk = tile % tiles_k, tv = tile / tiles_k, k0 = tk * 64, v0 = tv * 64;
;         {
;             const int v = t & 63, kk = t >> 6;
;             int L = v2logical(v0 + v);
;             if (mode) { const int g = (v0 + v) >= 2048 ? ((v0 + v) - 2048) >> 9 : -1; if (g == 2 || g == 6) L = v0 + v; }
;             const int col = mode ? inproj_actual(L) : coloff + L;
; #pragma unroll
;             for (int i = 0; i < 8; ++i) {
;                 const int k = kk + 8 * i;
;                 float xv = src[(size_t)(k0 + k) * ld + col];
;                 if (rowscale) xv *= rowscale[k0 + k];
;                 tl[k][v] = xv;
;             }
;         }
;         __syncthreads();
;         {
;             const int vv = t >> 3, kc = t & 7;
;             u32x4 o;
;             o[0] = pk2(tl[8 * kc + 0][vv], tl[8 * kc + 1][vv]); o[1] = pk2(tl[8 * kc + 2][vv], tl[8 * kc + 3][vv]);
;             o[2] = pk2(tl[8 * kc + 4][vv], tl[8 * kc + 5][vv]); o[3] = pk2(tl[8 * kc + 6][vv], tl[8 * kc + 7][vv]);
;             *(u32x4*)(dst + (size_t)(v0 + vv) * K + k0 + 8 * kc) = o;
;         }
;         __syncthreads();
;     }
.LBB0_433:
	s_ashr_i32 s12, s15, 31
	s_lshr_b32 s12, s12, 30
	s_add_i32 s12, s15, s12
	s_ashr_i32 s13, s12, 2
	s_lshl_b32 s12, s13, 8
	s_sub_i32 s12, s14, s12
	s_lshl_b32 s13, s13, 6
	v_or_b32_e32 v2, s13, v8
	v_add_u32_e32 v10, s12, v4
	v_ashrrev_i32_e32 v3, 31, v2
	v_ashrrev_i32_e32 v11, 31, v10
	v_lshl_add_u64 v[2:3], v[2:3], 2, s[6:7]
	v_lshlrev_b64 v[12:13], 12, v[10:11]
	v_lshl_add_u64 v[12:13], v[2:3], 0, v[12:13]
	global_load_dword v40, v[12:13], off
	v_add_u32_e32 v12, 8, v10
	v_ashrrev_i32_e32 v13, 31, v12
	v_lshlrev_b64 v[12:13], 12, v[12:13]
	v_lshl_add_u64 v[12:13], v[2:3], 0, v[12:13]
	s_add_i32 s15, s15, s2
	s_add_i32 s14, s14, s3
	global_load_dword v41, v[12:13], off
	v_add_u32_e32 v12, 16, v10
	v_ashrrev_i32_e32 v13, 31, v12
	v_lshlrev_b64 v[12:13], 12, v[12:13]
	v_lshl_add_u64 v[12:13], v[2:3], 0, v[12:13]
	global_load_dword v42, v[12:13], off
	v_add_u32_e32 v12, 24, v10
	v_ashrrev_i32_e32 v13, 31, v12
	v_lshlrev_b64 v[12:13], 12, v[12:13]
	v_lshl_add_u64 v[12:13], v[2:3], 0, v[12:13]
	global_load_dword v43, v[12:13], off
	v_add_u32_e32 v12, 32, v10
	v_ashrrev_i32_e32 v13, 31, v12
	v_lshlrev_b64 v[12:13], 12, v[12:13]
	v_lshl_add_u64 v[12:13], v[2:3], 0, v[12:13]
	global_load_dword v44, v[12:13], off
	v_add_u32_e32 v12, 40, v10
	v_ashrrev_i32_e32 v13, 31, v12
	v_lshlrev_b64 v[12:13], 12, v[12:13]
	v_lshl_add_u64 v[12:13], v[2:3], 0, v[12:13]
	global_load_dword v45, v[12:13], off
	v_add_u32_e32 v12, 48, v10
	v_add_u32_e32 v10, 56, v10
	v_ashrrev_i32_e32 v13, 31, v12
	v_ashrrev_i32_e32 v11, 31, v10
	v_lshlrev_b64 v[12:13], 12, v[12:13]
	v_lshlrev_b64 v[10:11], 12, v[10:11]
	v_lshl_add_u64 v[12:13], v[2:3], 0, v[12:13]
	v_lshl_add_u64 v[2:3], v[2:3], 0, v[10:11]
	global_load_dword v46, v[2:3], off
	global_load_dword v47, v[12:13], off
	s_waitcnt vmcnt(0)
	ds_write_b32 v7, v40
	ds_write_b32 v7, v41 offset:2080
	ds_write_b32 v7, v42 offset:4160
	ds_write_b32 v7, v43 offset:6240
	ds_write_b32 v7, v44 offset:8320
	ds_write_b32 v7, v45 offset:10400
	ds_write_b32 v7, v46 offset:14560
	ds_write_b32 v7, v47 offset:12480
	s_waitcnt lgkmcnt(0)
	s_barrier
	ds_read2_b32 v[2:3], v6 offset1:65
	v_add_u32_e32 v9, 0x400, v6
	s_waitcnt lgkmcnt(0)
	v_cvt_pk_bf16_f32 v10, v2, v3
	ds_read2_b32 v[2:3], v6 offset0:130 offset1:195
	s_waitcnt lgkmcnt(0)
	v_cvt_pk_bf16_f32 v11, v2, v3
	ds_read2_b32 v[2:3], v9 offset0:4 offset1:69
	s_waitcnt lgkmcnt(0)
	v_cvt_pk_bf16_f32 v12, v2, v3
	ds_read2_b32 v[2:3], v9 offset0:134 offset1:199
	s_waitcnt lgkmcnt(0)
	v_cvt_pk_bf16_f32 v13, v2, v3
	v_add_u32_e32 v2, s13, v5
	v_ashrrev_i32_e32 v3, 31, v2
	v_lshlrev_b64 v[2:3], 9, v[2:3]
	v_lshl_add_u64 v[2:3], s[10:11], 0, v[2:3]
	s_ashr_i32 s13, s12, 31
	v_lshl_add_u64 v[2:3], s[12:13], 1, v[2:3]
	v_lshl_add_u64 v[2:3], v[2:3], 0, v[0:1]
	s_cmp_lt_i32 s15, 64
	global_store_dwordx4 v[2:3], v[10:13], off
	s_barrier
	s_cbranch_scc1 .LBB0_433
	s_branch .LBB0_352
